# GEMM K-loop: removed the adjacent s_setprio 0 / s_setprio 1 pairs between the two 16-MFMA halves of each MFMA segment
# baseline (speedup 1.0000x reference)
; #define PG8_STAGE(bufoff, gbase, voff) do { _Pragma("unroll") for (int _i = 0; _i < 2; ++_i) \
;         __builtin_amdgcn_global_load_lds((const unsigned*)((const char*)(gbase) + (voff)[_i]), (PG8_LAS unsigned*)(lds + (bufoff) + ldsw + _i * 8192), 16, 0, 0); } while (0)
; #define PG8_LDA(dst, b, h) do { _Pragma("unroll") for (int m = 0; m < 4; ++m) _Pragma("unroll") for (int k = 0; k < 2; ++k) dst[m][k] = *(const PG8_LAS bf16x8*)(lds + PG8_SA(b, h) + aoff + m * 2048 + k * 1024); } while (0)
; #define PG8_MMA(ai, bj, At, Bt) do { __builtin_amdgcn_s_setprio(1); _Pragma("unroll") for (int m = 0; m < 4; ++m) _Pragma("unroll") for (int n = 0; n < 2; ++n) _Pragma("unroll") for (int k = 0; k < 2; ++k) \
;         acc[ai][bj][m][n] = __builtin_amdgcn_mfma_f32_16x16x32_bf16(Bt[n][k], At[m][k], acc[ai][bj][m][n], 0, 0, 0); __builtin_amdgcn_s_setprio(0); } while (0)
; #define PG8_WAIT_V(n) asm volatile("s_waitcnt vmcnt(" #n ")" ::: "memory")
; #define PG8_WAIT_L(n) asm volatile("s_waitcnt lgkmcnt(" #n ")" ::: "memory")
; #define PG8_BAR __builtin_amdgcn_s_barrier()
; #define PG8_SCHED __builtin_amdgcn_sched_barrier(0)
; template <class Epi, class Sched, bool ALIGN_EPI = false, bool SP2 = false>
; __device__ __forceinline__ void gemm_phase(PG8_LAS unsigned char* lds, const Gemm g, const Sched& S, const Epi& E, const int tid) {
;     ...
;             PG8_WAIT_V(8); PG8_WAIT_L(0); PG8_BAR; PG8_MMA(0, 0, At, B0); PG8_MMA(0, 1, At, B1); PG8_BAR; PG8_SCHED;
;             PG8_LDA(At, 0, 1); PG8_STAGE(PG8_SB(0, 0), b2, voffB); PG8_STAGE(PG8_SB(0, 1), b2 + hstepB, voffB); PG8_STAGE(PG8_SA(0, 0), a2, voffA);
.Lg_done1:
	s_waitcnt lgkmcnt(0)
	s_barrier
	s_setprio 1
	s_waitcnt lgkmcnt(0)
	v_mfma_f32_16x16x32_bf16 v[126:129], v[150:153], v[212:215], v[126:129]
	v_mfma_f32_16x16x32_bf16 v[122:125], v[164:167], v[212:215], v[122:125]
	v_mfma_f32_16x16x32_bf16 v[118:121], v[150:153], v[220:223], v[118:121]
	v_mfma_f32_16x16x32_bf16 v[114:117], v[164:167], v[220:223], v[114:117]
	v_mfma_f32_16x16x32_bf16 v[106:109], v[150:153], v[228:231], v[106:109]
	v_mfma_f32_16x16x32_bf16 v[98:101], v[164:167], v[228:231], v[98:101]
	v_mfma_f32_16x16x32_bf16 v[90:93], v[150:153], v[236:239], v[90:93]
	v_mfma_f32_16x16x32_bf16 v[82:85], v[164:167], v[236:239], v[82:85]
	v_mfma_f32_16x16x32_bf16 v[126:129], v[160:163], v[216:219], v[126:129]
	v_mfma_f32_16x16x32_bf16 v[122:125], v[168:171], v[216:219], v[122:125]
	v_mfma_f32_16x16x32_bf16 v[118:121], v[160:163], v[224:227], v[118:121]
	v_mfma_f32_16x16x32_bf16 v[114:117], v[168:171], v[224:227], v[114:117]
	v_mfma_f32_16x16x32_bf16 v[106:109], v[160:163], v[232:235], v[106:109]
	v_mfma_f32_16x16x32_bf16 v[98:101], v[168:171], v[232:235], v[98:101]
	v_mfma_f32_16x16x32_bf16 v[90:93], v[160:163], v[240:243], v[90:93]
	v_mfma_f32_16x16x32_bf16 v[82:85], v[168:171], v[240:243], v[82:85]
	v_mfma_f32_16x16x32_bf16 v[110:113], v[172:175], v[212:215], v[110:113]
	v_mfma_f32_16x16x32_bf16 v[102:105], v[180:183], v[212:215], v[102:105]
	v_mfma_f32_16x16x32_bf16 v[94:97], v[172:175], v[220:223], v[94:97]
	v_mfma_f32_16x16x32_bf16 v[86:89], v[180:183], v[220:223], v[86:89]
	v_mfma_f32_16x16x32_bf16 v[78:81], v[172:175], v[228:231], v[78:81]
	v_mfma_f32_16x16x32_bf16 v[74:77], v[180:183], v[228:231], v[74:77]
	v_mfma_f32_16x16x32_bf16 v[70:73], v[172:175], v[236:239], v[70:73]
	v_mfma_f32_16x16x32_bf16 v[66:69], v[180:183], v[236:239], v[66:69]
	v_mfma_f32_16x16x32_bf16 v[110:113], v[176:179], v[216:219], v[110:113]
	v_mfma_f32_16x16x32_bf16 v[102:105], v[208:211], v[216:219], v[102:105]
	v_mfma_f32_16x16x32_bf16 v[94:97], v[176:179], v[224:227], v[94:97]
	v_mfma_f32_16x16x32_bf16 v[86:89], v[208:211], v[224:227], v[86:89]
	v_mfma_f32_16x16x32_bf16 v[78:81], v[176:179], v[232:235], v[78:81]
	v_mfma_f32_16x16x32_bf16 v[74:77], v[208:211], v[232:235], v[74:77]
	v_mfma_f32_16x16x32_bf16 v[70:73], v[176:179], v[240:243], v[70:73]
	v_mfma_f32_16x16x32_bf16 v[66:69], v[208:211], v[240:243], v[66:69]
	s_setprio 0
	s_barrier
	s_add_i32 s22, s22, s43
	v_lshl_add_u64 v[144:145], vcc, 0, v[134:135]
	s_mov_b32 m0, s22
	ds_read_b128 v[212:215], v158 offset:16384
	ds_read_b128 v[216:219], v158 offset:17408
	ds_read_b128 v[220:223], v158 offset:18432
	ds_read_b128 v[224:227], v158 offset:19456
	ds_read_b128 v[228:231], v158 offset:20480
	ds_read_b128 v[232:235], v158 offset:21504
	ds_read_b128 v[236:239], v158 offset:22528
	ds_read_b128 v[240:243], v158 offset:23552
	global_load_lds_dwordx4 v[144:145], off
	s_add_i32 m0, s22, 0x2000
	v_lshl_add_u64 v[154:155], vcc, 0, v[130:131]
	s_add_u32 vcc_lo, vcc_lo, s41
	s_addc_u32 vcc_hi, vcc_hi, 0
	s_add_i32 s22, s23, s43
	global_load_lds_dwordx4 v[154:155], off
	v_lshl_add_u64 v[184:185], vcc, 0, v[134:135]
	s_mov_b32 m0, s22
	v_lshl_add_u64 v[244:245], vcc, 0, v[130:131]
	global_load_lds_dwordx4 v[184:185], off
	s_add_i32 m0, s22, 0x2000
	v_lshl_add_u64 v[246:247], s[56:57], 0, v[136:137]
	global_load_lds_dwordx4 v[244:245], off
	s_mov_b32 m0, s96
	v_lshl_add_u64 v[248:249], s[56:57], 0, v[132:133]
	global_load_lds_dwordx4 v[246:247], off
	s_mov_b32 m0, s97
	s_nop 0
	global_load_lds_dwordx4 v[248:249], off
	s_cmp_eq_u32 s100, 0
	s_cbranch_scc1 .Lg_norm2
	s_sub_u32 s100, s100, 1
	s_waitcnt vmcnt(24)
	s_branch .Lg_done2

; #define PG8_STAGE(bufoff, gbase, voff) do { _Pragma("unroll") for (int _i = 0; _i < 2; ++_i) \
;         __builtin_amdgcn_global_load_lds((const unsigned*)((const char*)(gbase) + (voff)[_i]), (PG8_LAS unsigned*)(lds + (bufoff) + ldsw + _i * 8192), 16, 0, 0); } while (0)
; #define PG8_LDA(dst, b, h) do { _Pragma("unroll") for (int m = 0; m < 4; ++m) _Pragma("unroll") for (int k = 0; k < 2; ++k) dst[m][k] = *(const PG8_LAS bf16x8*)(lds + PG8_SA(b, h) + aoff + m * 2048 + k * 1024); } while (0)
; #define PG8_LDB(dst, b, h) do { _Pragma("unroll") for (int n = 0; n < 2; ++n) _Pragma("unroll") for (int k = 0; k < 2; ++k) dst[n][k] = *(const PG8_LAS bf16x8*)(lds + PG8_SB(b, h) + boff + n * 2048 + k * 1024); } while (0)
; #define PG8_MMA(ai, bj, At, Bt) do { __builtin_amdgcn_s_setprio(1); _Pragma("unroll") for (int m = 0; m < 4; ++m) _Pragma("unroll") for (int n = 0; n < 2; ++n) _Pragma("unroll") for (int k = 0; k < 2; ++k) \
;         acc[ai][bj][m][n] = __builtin_amdgcn_mfma_f32_16x16x32_bf16(Bt[n][k], At[m][k], acc[ai][bj][m][n], 0, 0, 0); __builtin_amdgcn_s_setprio(0); } while (0)
; #define PG8_WAIT_V(n) asm volatile("s_waitcnt vmcnt(" #n ")" ::: "memory")
; #define PG8_WAIT_L(n) asm volatile("s_waitcnt lgkmcnt(" #n ")" ::: "memory")
; #define PG8_BAR __builtin_amdgcn_s_barrier()
; #define PG8_SCHED __builtin_amdgcn_sched_barrier(0)
; template <class Epi, class Sched, bool ALIGN_EPI = false, bool SP2 = false>
; __device__ __forceinline__ void gemm_phase(PG8_LAS unsigned char* lds, const Gemm g, const Sched& S, const Epi& E, const int tid) {
;     ...
;             PG8_WAIT_V(8); PG8_WAIT_L(0); PG8_BAR; PG8_MMA(1, 0, At, B0); PG8_MMA(1, 1, At, B1); PG8_BAR; PG8_SCHED;
;             PG8_LDB(B0, 1, 0); PG8_LDB(B1, 1, 1); PG8_SCHED; PG8_LDA(At, 1, 0); PG8_STAGE(PG8_SA(0, 1), a2 + hstepA, voffA);
;             PG8_WAIT_V(8); PG8_WAIT_L(0); PG8_BAR; PG8_MMA(0, 0, At, B0); PG8_MMA(0, 1, At, B1); PG8_BAR; PG8_SCHED;
.Lg_done2:
	s_waitcnt lgkmcnt(0)
	s_barrier
	s_setprio 1
	s_waitcnt lgkmcnt(0)
	v_mfma_f32_16x16x32_bf16 v[62:65], v[150:153], v[212:215], v[62:65]
	v_mfma_f32_16x16x32_bf16 v[58:61], v[164:167], v[212:215], v[58:61]
	v_mfma_f32_16x16x32_bf16 v[54:57], v[150:153], v[220:223], v[54:57]
	v_mfma_f32_16x16x32_bf16 v[50:53], v[164:167], v[220:223], v[50:53]
	v_mfma_f32_16x16x32_bf16 v[42:45], v[150:153], v[228:231], v[42:45]
	v_mfma_f32_16x16x32_bf16 v[34:37], v[164:167], v[228:231], v[34:37]
	v_mfma_f32_16x16x32_bf16 v[26:29], v[150:153], v[236:239], v[26:29]
	v_mfma_f32_16x16x32_bf16 v[18:21], v[164:167], v[236:239], v[18:21]
	v_mfma_f32_16x16x32_bf16 v[62:65], v[160:163], v[216:219], v[62:65]
	v_mfma_f32_16x16x32_bf16 v[58:61], v[168:171], v[216:219], v[58:61]
	v_mfma_f32_16x16x32_bf16 v[54:57], v[160:163], v[224:227], v[54:57]
	v_mfma_f32_16x16x32_bf16 v[50:53], v[168:171], v[224:227], v[50:53]
	v_mfma_f32_16x16x32_bf16 v[42:45], v[160:163], v[232:235], v[42:45]
	v_mfma_f32_16x16x32_bf16 v[34:37], v[168:171], v[232:235], v[34:37]
	v_mfma_f32_16x16x32_bf16 v[26:29], v[160:163], v[240:243], v[26:29]
	v_mfma_f32_16x16x32_bf16 v[18:21], v[168:171], v[240:243], v[18:21]
	v_mfma_f32_16x16x32_bf16 v[46:49], v[172:175], v[212:215], v[46:49]
	v_mfma_f32_16x16x32_bf16 v[38:41], v[180:183], v[212:215], v[38:41]
	v_mfma_f32_16x16x32_bf16 v[30:33], v[172:175], v[220:223], v[30:33]
	v_mfma_f32_16x16x32_bf16 v[22:25], v[180:183], v[220:223], v[22:25]
	v_mfma_f32_16x16x32_bf16 v[14:17], v[172:175], v[228:231], v[14:17]
	v_mfma_f32_16x16x32_bf16 v[10:13], v[180:183], v[228:231], v[10:13]
	v_mfma_f32_16x16x32_bf16 v[6:9], v[172:175], v[236:239], v[6:9]
	v_mfma_f32_16x16x32_bf16 v[2:5], v[180:183], v[236:239], v[2:5]
	v_mfma_f32_16x16x32_bf16 v[46:49], v[176:179], v[216:219], v[46:49]
	v_mfma_f32_16x16x32_bf16 v[38:41], v[208:211], v[216:219], v[38:41]
	v_mfma_f32_16x16x32_bf16 v[30:33], v[176:179], v[224:227], v[30:33]
	v_mfma_f32_16x16x32_bf16 v[22:25], v[208:211], v[224:227], v[22:25]
	v_mfma_f32_16x16x32_bf16 v[14:17], v[176:179], v[232:235], v[14:17]
	v_mfma_f32_16x16x32_bf16 v[10:13], v[208:211], v[232:235], v[10:13]
	v_mfma_f32_16x16x32_bf16 v[6:9], v[176:179], v[240:243], v[6:9]
	v_mfma_f32_16x16x32_bf16 v[2:5], v[208:211], v[240:243], v[2:5]
	s_setprio 0
	s_barrier
	s_add_i32 s22, 0, 0x18000
	v_add_u32_e32 v159, s22, v156
	s_add_i32 s23, 0, 0x1c000
	ds_read_b128 v[150:153], v159
	ds_read_b128 v[160:163], v159 offset:1024
	ds_read_b128 v[164:167], v159 offset:2048
	ds_read_b128 v[168:171], v159 offset:3072
	v_add_u32_e32 v159, s23, v156
	ds_read_b128 v[172:175], v159
	ds_read_b128 v[176:179], v159 offset:1024
	ds_read_b128 v[180:183], v159 offset:2048
	ds_read_b128 v[208:211], v159 offset:3072
	s_add_u32 s56, s56, s50
	s_addc_u32 s57, s57, 0
	s_mov_b32 m0, s0
	v_lshl_add_u64 v[250:251], s[56:57], 0, v[136:137]
	ds_read_b128 v[212:215], v158 offset:32768
	ds_read_b128 v[216:219], v158 offset:33792
	ds_read_b128 v[220:223], v158 offset:34816
	ds_read_b128 v[224:227], v158 offset:35840
	ds_read_b128 v[228:231], v158 offset:36864
	ds_read_b128 v[232:235], v158 offset:37888
	ds_read_b128 v[236:239], v158 offset:38912
	ds_read_b128 v[240:243], v158 offset:39936
	global_load_lds_dwordx4 v[250:251], off
	v_lshl_add_u64 v[250:251], s[56:57], 0, v[132:133]
	s_mov_b32 m0, s1
	s_nop 0
	global_load_lds_dwordx4 v[250:251], off
	s_waitcnt vmcnt(8)
	s_waitcnt lgkmcnt(0)
	s_barrier
	s_setprio 1
	s_waitcnt lgkmcnt(0)
	v_mfma_f32_16x16x32_bf16 v[126:129], v[150:153], v[212:215], v[126:129]
	v_mfma_f32_16x16x32_bf16 v[122:125], v[164:167], v[212:215], v[122:125]
	v_mfma_f32_16x16x32_bf16 v[118:121], v[150:153], v[220:223], v[118:121]
	v_mfma_f32_16x16x32_bf16 v[114:117], v[164:167], v[220:223], v[114:117]
	v_mfma_f32_16x16x32_bf16 v[106:109], v[150:153], v[228:231], v[106:109]
	v_mfma_f32_16x16x32_bf16 v[98:101], v[164:167], v[228:231], v[98:101]
	v_mfma_f32_16x16x32_bf16 v[90:93], v[150:153], v[236:239], v[90:93]
	v_mfma_f32_16x16x32_bf16 v[82:85], v[164:167], v[236:239], v[82:85]
	v_mfma_f32_16x16x32_bf16 v[126:129], v[160:163], v[216:219], v[126:129]
	v_mfma_f32_16x16x32_bf16 v[122:125], v[168:171], v[216:219], v[122:125]
	v_mfma_f32_16x16x32_bf16 v[118:121], v[160:163], v[224:227], v[118:121]
	v_mfma_f32_16x16x32_bf16 v[114:117], v[168:171], v[224:227], v[114:117]
	v_mfma_f32_16x16x32_bf16 v[106:109], v[160:163], v[232:235], v[106:109]
	v_mfma_f32_16x16x32_bf16 v[98:101], v[168:171], v[232:235], v[98:101]
	v_mfma_f32_16x16x32_bf16 v[90:93], v[160:163], v[240:243], v[90:93]
	v_mfma_f32_16x16x32_bf16 v[82:85], v[168:171], v[240:243], v[82:85]
	v_mfma_f32_16x16x32_bf16 v[110:113], v[172:175], v[212:215], v[110:113]
	v_mfma_f32_16x16x32_bf16 v[102:105], v[180:183], v[212:215], v[102:105]
	v_mfma_f32_16x16x32_bf16 v[94:97], v[172:175], v[220:223], v[94:97]
	v_mfma_f32_16x16x32_bf16 v[86:89], v[180:183], v[220:223], v[86:89]
	v_mfma_f32_16x16x32_bf16 v[78:81], v[172:175], v[228:231], v[78:81]
	v_mfma_f32_16x16x32_bf16 v[74:77], v[180:183], v[228:231], v[74:77]
	v_mfma_f32_16x16x32_bf16 v[70:73], v[172:175], v[236:239], v[70:73]
	v_mfma_f32_16x16x32_bf16 v[66:69], v[180:183], v[236:239], v[66:69]
	v_mfma_f32_16x16x32_bf16 v[110:113], v[176:179], v[216:219], v[110:113]
	v_mfma_f32_16x16x32_bf16 v[102:105], v[208:211], v[216:219], v[102:105]
	v_mfma_f32_16x16x32_bf16 v[94:97], v[176:179], v[224:227], v[94:97]
	v_mfma_f32_16x16x32_bf16 v[86:89], v[208:211], v[224:227], v[86:89]
	v_mfma_f32_16x16x32_bf16 v[78:81], v[176:179], v[232:235], v[78:81]
	v_mfma_f32_16x16x32_bf16 v[74:77], v[208:211], v[232:235], v[74:77]
	v_mfma_f32_16x16x32_bf16 v[70:73], v[176:179], v[240:243], v[70:73]
	v_mfma_f32_16x16x32_bf16 v[66:69], v[208:211], v[240:243], v[66:69]
	s_setprio 0
	s_barrier
; #define PG8_STAGE(bufoff, gbase, voff) do { _Pragma("unroll") for (int _i = 0; _i < 2; ++_i) \
;         __builtin_amdgcn_global_load_lds((const unsigned*)((const char*)(gbase) + (voff)[_i]), (PG8_LAS unsigned*)(lds + (bufoff) + ldsw + _i * 8192), 16, 0, 0); } while (0)
; #define PG8_LDA(dst, b, h) do { _Pragma("unroll") for (int m = 0; m < 4; ++m) _Pragma("unroll") for (int k = 0; k < 2; ++k) dst[m][k] = *(const PG8_LAS bf16x8*)(lds + PG8_SA(b, h) + aoff + m * 2048 + k * 1024); } while (0)
; #define PG8_MMA(ai, bj, At, Bt) do { __builtin_amdgcn_s_setprio(1); _Pragma("unroll") for (int m = 0; m < 4; ++m) _Pragma("unroll") for (int n = 0; n < 2; ++n) _Pragma("unroll") for (int k = 0; k < 2; ++k) \
;         acc[ai][bj][m][n] = __builtin_amdgcn_mfma_f32_16x16x32_bf16(Bt[n][k], At[m][k], acc[ai][bj][m][n], 0, 0, 0); __builtin_amdgcn_s_setprio(0); } while (0)
; #define PG8_WAIT_V(n) asm volatile("s_waitcnt vmcnt(" #n ")" ::: "memory")
; #define PG8_WAIT_L(n) asm volatile("s_waitcnt lgkmcnt(" #n ")" ::: "memory")
; #define PG8_BAR __builtin_amdgcn_s_barrier()
; #define PG8_SCHED __builtin_amdgcn_sched_barrier(0)
;     __device__ __forceinline__ void operator()(const f32x4 (&acc)[2][2][4][2], const Unit& u, int wr, int wc, int fr, int fq) const {
;     ...
;                 for (int bj = 0; bj < 2; ++bj) { f32x4 v0 = acc[ai][bj][m][0] + bv[bj][0], v1 = acc[ai][bj][m][1] + bv[bj][1];
; template <class Epi, class Sched, bool ALIGN_EPI = false, bool SP2 = false>
; __device__ __forceinline__ void gemm_phase(PG8_LAS unsigned char* lds, const Gemm g, const Sched& S, const Epi& E, const int tid) {
;     ...
;             PG8_LDA(At, 1, 1); PG8_STAGE(PG8_SB(1, 0), b3, voffB); PG8_STAGE(PG8_SB(1, 1), b3 + hstepB, voffB); PG8_STAGE(PG8_SA(1, 0), a3, voffA);
;             PG8_WAIT_V(8); PG8_WAIT_L(0); PG8_BAR; PG8_MMA(1, 0, At, B0); PG8_MMA(1, 1, At, B1); PG8_BAR; PG8_SCHED;
	s_add_i32 s22, s22, s43
	v_lshl_add_u64 v[144:145], v[144:145], 0, s[52:53]
	s_mov_b32 m0, s22
	ds_read_b128 v[212:215], v158 offset:49152
	ds_read_b128 v[216:219], v158 offset:50176
	ds_read_b128 v[220:223], v158 offset:51200
	ds_read_b128 v[224:227], v158 offset:52224
	ds_read_b128 v[228:231], v158 offset:53248
	ds_read_b128 v[232:235], v158 offset:54272
	ds_read_b128 v[236:239], v158 offset:55296
	ds_read_b128 v[240:243], v158 offset:56320
	global_load_lds_dwordx4 v[144:145], off
	v_lshl_add_u64 v[144:145], v[154:155], 0, s[52:53]
	s_add_i32 m0, s22, 0x2000
	s_add_i32 s22, s23, s43
	global_load_lds_dwordx4 v[144:145], off
	v_lshl_add_u64 v[144:145], v[184:185], 0, s[52:53]
	s_mov_b32 m0, s22
	s_nop 0
	global_load_lds_dwordx4 v[144:145], off
	v_lshl_add_u64 v[144:145], v[244:245], 0, s[52:53]
	s_add_i32 m0, s22, 0x2000
	s_nop 0
	global_load_lds_dwordx4 v[144:145], off
	v_lshl_add_u64 v[144:145], v[246:247], 0, s[52:53]
	s_mov_b32 m0, s98
	s_nop 0
	global_load_lds_dwordx4 v[144:145], off
	v_lshl_add_u64 v[144:145], v[248:249], 0, s[52:53]
	s_mov_b32 m0, s99
	s_nop 0
	global_load_lds_dwordx4 v[144:145], off
	s_waitcnt vmcnt(8)
	s_waitcnt lgkmcnt(0)
	s_barrier
	s_setprio 1
	s_waitcnt lgkmcnt(0)
	v_mfma_f32_16x16x32_bf16 v[62:65], v[150:153], v[212:215], v[62:65]
	v_mfma_f32_16x16x32_bf16 v[58:61], v[164:167], v[212:215], v[58:61]
	v_mfma_f32_16x16x32_bf16 v[54:57], v[150:153], v[220:223], v[54:57]
	v_mfma_f32_16x16x32_bf16 v[50:53], v[164:167], v[220:223], v[50:53]
	v_mfma_f32_16x16x32_bf16 v[42:45], v[150:153], v[228:231], v[42:45]
	v_mfma_f32_16x16x32_bf16 v[34:37], v[164:167], v[228:231], v[34:37]
	v_mfma_f32_16x16x32_bf16 v[26:29], v[150:153], v[236:239], v[26:29]
	v_mfma_f32_16x16x32_bf16 v[18:21], v[164:167], v[236:239], v[18:21]
	v_mfma_f32_16x16x32_bf16 v[62:65], v[160:163], v[216:219], v[62:65]
	v_mfma_f32_16x16x32_bf16 v[58:61], v[168:171], v[216:219], v[58:61]
	v_mfma_f32_16x16x32_bf16 v[54:57], v[160:163], v[224:227], v[54:57]
	v_mfma_f32_16x16x32_bf16 v[50:53], v[168:171], v[224:227], v[50:53]
	v_mfma_f32_16x16x32_bf16 v[42:45], v[160:163], v[232:235], v[42:45]
	v_mfma_f32_16x16x32_bf16 v[34:37], v[168:171], v[232:235], v[34:37]
	v_mfma_f32_16x16x32_bf16 v[26:29], v[160:163], v[240:243], v[26:29]
	v_mfma_f32_16x16x32_bf16 v[18:21], v[168:171], v[240:243], v[18:21]
	v_mfma_f32_16x16x32_bf16 v[46:49], v[172:175], v[212:215], v[46:49]
	v_mfma_f32_16x16x32_bf16 v[38:41], v[180:183], v[212:215], v[38:41]
	v_mfma_f32_16x16x32_bf16 v[30:33], v[172:175], v[220:223], v[30:33]
	v_mfma_f32_16x16x32_bf16 v[22:25], v[180:183], v[220:223], v[22:25]
	v_mfma_f32_16x16x32_bf16 v[14:17], v[172:175], v[228:231], v[14:17]
	v_mfma_f32_16x16x32_bf16 v[10:13], v[180:183], v[228:231], v[10:13]
	v_mfma_f32_16x16x32_bf16 v[6:9], v[172:175], v[236:239], v[6:9]
	v_mfma_f32_16x16x32_bf16 v[2:5], v[180:183], v[236:239], v[2:5]
	v_mfma_f32_16x16x32_bf16 v[46:49], v[176:179], v[216:219], v[46:49]
	v_mfma_f32_16x16x32_bf16 v[38:41], v[208:211], v[216:219], v[38:41]
	v_mfma_f32_16x16x32_bf16 v[30:33], v[176:179], v[224:227], v[30:33]
	v_mfma_f32_16x16x32_bf16 v[22:25], v[208:211], v[224:227], v[22:25]
	v_mfma_f32_16x16x32_bf16 v[14:17], v[176:179], v[232:235], v[14:17]
	v_mfma_f32_16x16x32_bf16 v[10:13], v[208:211], v[232:235], v[10:13]
	v_mfma_f32_16x16x32_bf16 v[6:9], v[176:179], v[240:243], v[6:9]
	v_mfma_f32_16x16x32_bf16 v[2:5], v[208:211], v[240:243], v[2:5]
	s_setprio 0
	s_barrier
	s_add_u32 s90, s90, 0x100
	s_addc_u32 s91, s91, 0
	s_add_u32 s25, s25, 0x100
	s_addc_u32 s92, s92, 0
	s_cmp_ge_u32 s93, s33
	s_mov_b32 s56, s93
	s_cbranch_scc0 .LBB0_67
	v_pk_add_f32 v[128:129], v[128:129], 0 op_sel_hi:[1,0]
	v_pk_add_f32 v[126:127], v[126:127], 0 op_sel_hi:[1,0]
	v_pk_add_f32 v[124:125], v[124:125], 0 op_sel_hi:[1,0]
	v_pk_add_f32 v[122:123], v[122:123], 0 op_sel_hi:[1,0]
	v_pk_add_f32 v[144:145], v[112:113], 0 op_sel_hi:[1,0]
	v_pk_add_f32 v[150:151], v[110:111], 0 op_sel_hi:[1,0]
	v_pk_add_f32 v[152:153], v[104:105], 0 op_sel_hi:[1,0]
	v_pk_add_f32 v[154:155], v[102:103], 0 op_sel_hi:[1,0]
	v_pk_add_f32 v[102:103], v[120:121], 0 op_sel_hi:[1,0]
	v_pk_add_f32 v[104:105], v[118:119], 0 op_sel_hi:[1,0]
	v_pk_add_f32 v[110:111], v[116:117], 0 op_sel_hi:[1,0]
	v_pk_add_f32 v[112:113], v[114:115], 0 op_sel_hi:[1,0]
	v_pk_add_f32 v[114:115], v[96:97], 0 op_sel_hi:[1,0]
	v_pk_add_f32 v[116:117], v[94:95], 0 op_sel_hi:[1,0]
	v_pk_add_f32 v[118:119], v[88:89], 0 op_sel_hi:[1,0]
	v_pk_add_f32 v[120:121], v[86:87], 0 op_sel_hi:[1,0]
	v_pk_add_f32 v[86:87], v[108:109], 0 op_sel_hi:[1,0]
	v_pk_add_f32 v[88:89], v[106:107], 0 op_sel_hi:[1,0]
	v_pk_add_f32 v[94:95], v[100:101], 0 op_sel_hi:[1,0]
	v_pk_add_f32 v[96:97], v[98:99], 0 op_sel_hi:[1,0]
	v_pk_add_f32 v[98:99], v[80:81], 0 op_sel_hi:[1,0]
	v_pk_add_f32 v[100:101], v[78:79], 0 op_sel_hi:[1,0]
	v_pk_add_f32 v[106:107], v[76:77], 0 op_sel_hi:[1,0]
	v_pk_add_f32 v[108:109], v[74:75], 0 op_sel_hi:[1,0]
	v_pk_add_f32 v[74:75], v[92:93], 0 op_sel_hi:[1,0]
	v_pk_add_f32 v[76:77], v[90:91], 0 op_sel_hi:[1,0]
	v_pk_add_f32 v[78:79], v[84:85], 0 op_sel_hi:[1,0]
	v_pk_add_f32 v[80:81], v[82:83], 0 op_sel_hi:[1,0]
	v_pk_add_f32 v[72:73], v[72:73], 0 op_sel_hi:[1,0]
	v_pk_add_f32 v[70:71], v[70:71], 0 op_sel_hi:[1,0]
	v_pk_add_f32 v[68:69], v[68:69], 0 op_sel_hi:[1,0]
	v_pk_add_f32 v[66:67], v[66:67], 0 op_sel_hi:[1,0]
	v_pk_add_f32 v[64:65], v[64:65], 0 op_sel_hi:[1,0]
	v_pk_add_f32 v[62:63], v[62:63], 0 op_sel_hi:[1,0]
	v_pk_add_f32 v[60:61], v[60:61], 0 op_sel_hi:[1,0]
	v_pk_add_f32 v[58:59], v[58:59], 0 op_sel_hi:[1,0]
	v_pk_add_f32 v[82:83], v[48:49], 0 op_sel_hi:[1,0]
	v_pk_add_f32 v[84:85], v[46:47], 0 op_sel_hi:[1,0]
	v_pk_add_f32 v[90:91], v[40:41], 0 op_sel_hi:[1,0]
	v_pk_add_f32 v[92:93], v[38:39], 0 op_sel_hi:[1,0]
	v_pk_add_f32 v[38:39], v[56:57], 0 op_sel_hi:[1,0]
	v_pk_add_f32 v[40:41], v[54:55], 0 op_sel_hi:[1,0]
	v_pk_add_f32 v[46:47], v[52:53], 0 op_sel_hi:[1,0]
	v_pk_add_f32 v[48:49], v[50:51], 0 op_sel_hi:[1,0]
	v_pk_add_f32 v[50:51], v[32:33], 0 op_sel_hi:[1,0]
	v_pk_add_f32 v[52:53], v[30:31], 0 op_sel_hi:[1,0]
	v_pk_add_f32 v[54:55], v[24:25], 0 op_sel_hi:[1,0]
	v_pk_add_f32 v[56:57], v[22:23], 0 op_sel_hi:[1,0]
	v_pk_add_f32 v[22:23], v[44:45], 0 op_sel_hi:[1,0]
	v_pk_add_f32 v[24:25], v[42:43], 0 op_sel_hi:[1,0]
	v_pk_add_f32 v[30:31], v[36:37], 0 op_sel_hi:[1,0]
	v_pk_add_f32 v[32:33], v[34:35], 0 op_sel_hi:[1,0]
	v_pk_add_f32 v[34:35], v[16:17], 0 op_sel_hi:[1,0]
	v_pk_add_f32 v[36:37], v[14:15], 0 op_sel_hi:[1,0]
	v_pk_add_f32 v[42:43], v[12:13], 0 op_sel_hi:[1,0]
	v_pk_add_f32 v[44:45], v[10:11], 0 op_sel_hi:[1,0]
	v_pk_add_f32 v[10:11], v[28:29], 0 op_sel_hi:[1,0]
	v_pk_add_f32 v[12:13], v[26:27], 0 op_sel_hi:[1,0]
	v_pk_add_f32 v[14:15], v[20:21], 0 op_sel_hi:[1,0]
	v_pk_add_f32 v[16:17], v[18:19], 0 op_sel_hi:[1,0]
	v_pk_add_f32 v[8:9], v[8:9], 0 op_sel_hi:[1,0]
	v_pk_add_f32 v[6:7], v[6:7], 0 op_sel_hi:[1,0]
	v_pk_add_f32 v[4:5], v[4:5], 0 op_sel_hi:[1,0]
	v_pk_add_f32 v[2:3], v[2:3], 0 op_sel_hi:[1,0]
